# safety: drain VMEM/LDS before the extra SGU unit at the end of mix_b (no functional change otherwise)
# baseline (speedup 1.0000x reference)
.LBB0_1305:
	s_sub_u32 s0, s82, 232
	s_cmp_lt_u32 s0, 24
	s_cbranch_scc0 .Lmixb_back
	s_add_u32 s10, s0, 0x200
	s_add_u32 s1, s0, 0x2f4
	s_cmp_lt_u32 s0, 12
	s_cselect_b32 s10, s10, s1
	s_mov_b32 s100, 0xffffffff
	s_mov_b32 s101, 0
	s_waitcnt vmcnt(0) lgkmcnt(0)
	s_branch .Lsgu_extra
